# mla_norm: rotary-key load issued with the other row loads (one memory latency less per row), counted vmcnt
# baseline (speedup 1.0000x reference)
; __device__ __forceinline__ unsigned pack2(float a, float b) { unsigned r; asm("s_nop 1\n\tv_cvt_pk_bf16_f32 %0, %1, %2" : "=v"(r) : "v"(a), "v"(b)); return r; }
; __device__ __forceinline__ float bf2f(bf16_t b) { return __uint_as_float(((unsigned)b) << 16); }
; __device__ __forceinline__ void mla_norm_phase(const Params& p) {
;     ...
;   for (int row = blockIdx.x * 8 + wave; row < TALL; row += gridDim.x * 8) {
;     const bf16_t* dr = DOWN + (size_t)row * 512;
;     uint2 qv = *(const uint2*)(dr + lane * 4);
;     unsigned kvv = *(const unsigned*)(dr + 256 + lane * 2);
;     float q0 = bf2f(qv.x & 0xffff), q1 = bf2f(qv.x >> 16), q2 = bf2f(qv.y & 0xffff), q3 = bf2f(qv.y >> 16);
;     float k0 = bf2f(kvv & 0xffff), k1 = bf2f(kvv >> 16);
;     float sq = wave_sum(q0 * q0 + q1 * q1 + q2 * q2 + q3 * q3);
;     float sk = wave_sum(k0 * k0 + k1 * k1);
;     float rq = rsqrtf(sq * (1.f / 256.f) + 1e-6f), rk = rsqrtf(sk * (1.f / 128.f) + 1e-6f);
;     float4 g4 = *(const float4*)(gq + lane * 4); float2 g2 = *(const float2*)(gkv + lane * 2);
;     uint2 oq; oq.x = pack2(q0 * rq * g4.x, q1 * rq * g4.y); oq.y = pack2(q2 * rq * g4.z, q3 * rq * g4.w);
;     *(uint2*)(CQ + (size_t)row * 256 + lane * 4) = oq;
;     *(unsigned*)(CKV + (size_t)row * 128 + lane * 2) = pack2(k0 * rk * g2.x, k1 * rk * g2.y);
;     const int d = lane & 31;
;     float x = bf2f(dr[384 + d]);
;     float pr = __shfl_xor(x, 8);
;     const int pp = row % SALL;
;     if (pp >= NCTX) {
;       const int tp = pp - NCTX; const int type = d >> 4, isx2 = (d >> 3) & 1;
;       const float inv = exp2f(-(float)(d & 7) * (13.287712379549449f / 8.f));
;       const float pos = (float)(type ? (tp & 63) : (tp >> 6));
;       const float ang = pos * inv; const float cs = __cosf(ang), sn = __sinf(ang);
;       x = isx2 ? (x * cs + pr * sn) : (x * cs - pr * sn);
;     }
.LBB0_80:
	v_ashrrev_i32_e32 v1, 31, v0
	v_readlane_b32 s26, v254, 43
	v_lshlrev_b64 v[24:25], 10, v[0:1]
	v_readlane_b32 s27, v254, 44
	s_mov_b32 s2, 0x800000
	s_mov_b32 s7, 0x3e0f83e1
	v_lshl_add_u64 v[28:29], s[26:27], 0, v[24:25]
	v_lshl_add_u64 v[24:25], v[28:29], 0, v[10:11]
	global_load_dwordx2 v[30:31], v[24:25], off
	v_lshl_add_u64 v[24:25], v[28:29], 0, v[12:13]
	s_waitcnt lgkmcnt(0)
	global_load_dword v23, v[24:25], off offset:512
	s_nop 0
	global_load_dwordx4 v[24:27], v[2:3], off
	s_brev_b32 s26, 60
	s_mov_b32 s27, 0x3b800000
	v_lshl_add_u64 v[28:29], v[28:29], 0, v[14:15]
	global_load_ushort v44, v[28:29], off offset:768
	s_waitcnt vmcnt(3)
	v_lshlrev_b32_e32 v32, 16, v30
	v_and_b32_e32 v33, 0xffff0000, v30
	v_pk_mul_f32 v[36:37], v[32:33], v[32:33]
	v_lshlrev_b32_e32 v35, 16, v31
	v_and_b32_e32 v34, 0xffff0000, v31
	s_waitcnt vmcnt(2)
	v_lshlrev_b32_e32 v30, 16, v23
	v_and_b32_e32 v31, 0xffff0000, v23
	v_add_f32_e32 v36, v36, v37
	v_pk_mul_f32 v[38:39], v[34:35], v[34:35]
	v_pk_mul_f32 v[40:41], v[30:31], v[30:31]
	v_pk_fma_f32 v[36:37], v[34:35], v[34:35], v[36:37] op_sel_hi:[1,1,0]
	v_mov_b32_e32 v42, v40
	v_mov_b32_e32 v43, v38
	v_mov_b32_e32 v36, v41
	v_pk_add_f32 v[36:37], v[42:43], v[36:37]
	ds_bpermute_b32 v39, v16, v37
	ds_bpermute_b32 v38, v16, v36
	global_load_dwordx2 v[40:41], v[4:5], off
	s_waitcnt lgkmcnt(0)
	v_pk_add_f32 v[36:37], v[36:37], v[38:39]
	ds_bpermute_b32 v39, v17, v37
	ds_bpermute_b32 v38, v17, v36
	s_waitcnt lgkmcnt(0)
	v_pk_add_f32 v[36:37], v[36:37], v[38:39]
	ds_bpermute_b32 v39, v18, v37
	ds_bpermute_b32 v38, v18, v36
	s_waitcnt lgkmcnt(0)
	v_pk_add_f32 v[36:37], v[36:37], v[38:39]
	ds_bpermute_b32 v39, v19, v37
	ds_bpermute_b32 v38, v19, v36
	s_waitcnt lgkmcnt(0)
	v_pk_add_f32 v[36:37], v[36:37], v[38:39]
	ds_bpermute_b32 v39, v20, v37
	ds_bpermute_b32 v38, v20, v36
	s_waitcnt lgkmcnt(0)
	v_pk_add_f32 v[36:37], v[36:37], v[38:39]
	ds_bpermute_b32 v39, v21, v37
	ds_bpermute_b32 v38, v21, v36
	s_waitcnt lgkmcnt(0)
	v_pk_add_f32 v[36:37], v[36:37], v[38:39]
	s_nop 0
	v_pk_fma_f32 v[36:37], v[36:37], s[26:27], v[162:163] op_sel_hi:[1,1,0]
	v_lshlrev_b64 v[38:39], 9, v[0:1]
	v_mul_f32_e32 v23, 0x4b800000, v37
	v_cmp_gt_f32_e32 vcc, s2, v37
	v_lshl_add_u64 v[38:39], v[6:7], 0, v[38:39]
	s_nop 0
	v_cndmask_b32_e32 v23, v37, v23, vcc
	v_rsq_f32_e32 v23, v23
	s_nop 0
	v_mul_f32_e32 v37, 0x45800000, v23
	v_cndmask_b32_e32 v23, v23, v37, vcc
	v_mul_f32_e32 v32, v23, v32
	v_mul_f32_e32 v33, v23, v33
	v_mul_f32_e32 v35, v23, v35
	v_mul_f32_e32 v23, v23, v34
	s_waitcnt vmcnt(2)
	v_mul_f32_e32 v24, v24, v32
	v_mul_f32_e32 v25, v25, v33
	v_mul_f32_e32 v26, v26, v35
	v_mul_f32_e32 v23, v27, v23
	s_nop 1
	v_cvt_pk_bf16_f32 v24, v24, v25
	s_nop 1
	v_cvt_pk_bf16_f32 v25, v26, v23
	global_store_dwordx2 v[38:39], v[24:25], off
	v_mul_f32_e32 v24, 0x4b800000, v36
	v_cmp_gt_f32_e32 vcc, s2, v36
	v_mul_hi_i32 v26, v0, s7
	v_lshrrev_b32_e32 v28, 31, v26
	v_cndmask_b32_e32 v24, v36, v24, vcc
	v_rsq_f32_e32 v27, v24
	v_lshlrev_b64 v[24:25], 8, v[0:1]
	v_lshl_add_u64 v[24:25], v[8:9], 0, v[24:25]
	s_movk_i32 s2, 0xff
	v_mul_f32_e32 v1, 0x45800000, v27
	v_cndmask_b32_e32 v1, v27, v1, vcc
	v_mul_f32_e32 v27, v1, v30
	v_mul_f32_e32 v1, v1, v31
	s_waitcnt vmcnt(1)
	v_mul_f32_e32 v1, v41, v1
	v_mul_f32_e32 v27, v40, v27
	s_nop 1
	v_cvt_pk_bf16_f32 v1, v27, v1
	global_store_dword v[24:25], v1, off
	v_ashrrev_i32_e32 v24, 11, v26
	v_add_u32_e32 v24, v24, v28
	v_mul_i32_i24_e32 v24, 0x2100, v24
	v_sub_u32_e32 v24, v0, v24
	v_cmp_lt_i32_e32 vcc, s2, v24
	s_waitcnt vmcnt(1)
	v_lshlrev_b32_e32 v1, 16, v44
	ds_bpermute_b32 v23, v18, v1
	s_and_saveexec_b64 s[26:27], vcc
	s_cbranch_execz .LBB0_79
	v_add_u32_e32 v25, 0xffffff00, v24
	v_and_b32_e32 v24, 63, v24
	v_lshrrev_b32_e32 v25, 6, v25
	v_cndmask_b32_e64 v24, v24, v25, s[40:41]
	v_cvt_f32_u32_e32 v24, v24
	v_mul_f32_e32 v24, v22, v24
	v_mul_f32_e32 v24, 0.15915494, v24
	v_sin_f32_e32 v25, v24
	v_cos_f32_e32 v24, v24
	s_waitcnt lgkmcnt(0)
	v_mul_f32_e32 v23, v25, v23
	v_cndmask_b32_e64 v23, v23, -v23, s[42:43]
	v_fmac_f32_e32 v23, v24, v1
	v_mov_b32_e32 v1, v23
	s_branch .LBB0_79
